# P5: the last K iteration's dummy next-unit staging loads point at the unit's XN residual tile (L2 prefetch for the epilogue's LDS-DMA residual fetch)
# speedup vs baseline: 1.0105x; 1.0026x over previous
;     __host__ __device__ bool next(int i, Unit& u) const { return at((long)i * G + c, u); }
;     __host__ __device__ bool next(int i, Unit& u) const { if (i != 0 || c >= cnt) return false; u.pm = pm0 + c / nN; u.pn = c % nN; u.k0 = 0; u.nt = ntk; return true; }
;     ...
;         const bool has_next = S.next(ui + 1, nxt);
;         const char* nA = has_next ? (const char*)g.A + (size_t)nxt.pm * tstep + (size_t)nxt.k0 * (BK * 2) : cA; const char* nB = has_next ? (const char*)g.Bt + (size_t)nxt.pn * tstep + (size_t)nxt.k0 * (BK * 2) : cB;
;         const int nt = cur.nt;
;         for (int t = 0; t < nt; t += 2) {
;             const bool last = (t == nt - 2);
;             const char* a1 = cA + (size_t)(t + 1) * kstep;
;             const char* a2 = last ? nA : cA + (size_t)(t + 2) * kstep; const char* b2 = last ? nB : cB + (size_t)(t + 2) * kstep;
;             const char* a3 = a2 + kstep; const char* b3 = b2 + kstep;
.LBB0_853:
	s_ashr_i32 s25, s24, 31
	s_lshl_b64 s[26:27], s[24:25], 19
	s_add_u32 s26, s6, s26
	s_addc_u32 s27, s7, s27
	s_and_b64 s[28:29], s[4:5], exec
	s_cselect_b32 s15, s27, s35
	s_cselect_b32 s25, s26, s34
	s_ashr_i32 s23, s22, 31
	s_lshl_b64 s[28:29], s[22:23], 19
	s_add_u32 s28, s3, s28
	s_addc_u32 s29, s42, s29
	s_and_b64 s[38:39], s[4:5], exec
	s_cselect_b32 s23, s29, s37
	s_cselect_b32 s31, s28, s36
	s_sub_u32 s76, s34, s6
	s_sub_u32 s77, s36, s3
	s_lshr_b32 s77, s77, 10
	s_add_u32 s76, s76, s77
	s_add_u32 s76, s76, 0x1a00000
	s_add_u32 s98, s68, s76
	s_addc_u32 s99, s69, 0
	s_and_b64 s[38:39], s[4:5], exec
	s_cselect_b32 s25, s25, s98
	s_cselect_b32 s15, s15, s99
	s_add_u32 s98, s98, 0x100
	s_addc_u32 s99, s99, 0
	s_and_b64 s[38:39], s[4:5], exec
	s_cselect_b32 s31, s31, s98
	s_cselect_b32 s23, s23, s99
	s_add_u32 s34, s34, 0x40080
	s_addc_u32 s35, s35, 0
	s_add_u32 s56, s36, 0x100
	v_mov_b32_e32 v0, 0
	s_addc_u32 s57, s37, 0
	s_mov_b32 s58, -2
	s_waitcnt lgkmcnt(0)
	v_mov_b32_e32 v1, v0
	v_mov_b32_e32 v2, v0
	v_mov_b32_e32 v3, v0
	v_mov_b32_e32 v4, v0
	v_mov_b32_e32 v5, v0
	v_mov_b32_e32 v6, v0
	v_mov_b32_e32 v7, v0
	v_mov_b32_e32 v16, v0
	v_mov_b32_e32 v17, v0
	v_mov_b32_e32 v18, v0
	v_mov_b32_e32 v19, v0
	v_mov_b32_e32 v20, v0
	v_mov_b32_e32 v21, v0
	v_mov_b32_e32 v22, v0
	v_mov_b32_e32 v23, v0
	v_mov_b32_e32 v32, v0
	v_mov_b32_e32 v33, v0
	v_mov_b32_e32 v34, v0
	v_mov_b32_e32 v35, v0
	v_mov_b32_e32 v36, v0
	v_mov_b32_e32 v37, v0
	v_mov_b32_e32 v38, v0
	v_mov_b32_e32 v39, v0
	v_mov_b32_e32 v48, v0
	v_mov_b32_e32 v49, v0
	v_mov_b32_e32 v50, v0
	v_mov_b32_e32 v51, v0
	v_mov_b32_e32 v52, v0
	v_mov_b32_e32 v53, v0
	v_mov_b32_e32 v54, v0
	v_mov_b32_e32 v55, v0
	v_mov_b32_e32 v8, v0
	v_mov_b32_e32 v9, v0
	v_mov_b32_e32 v10, v0
	v_mov_b32_e32 v11, v0
	v_mov_b32_e32 v12, v0
	v_mov_b32_e32 v13, v0
	v_mov_b32_e32 v14, v0
	v_mov_b32_e32 v15, v0
	v_mov_b32_e32 v24, v0
	v_mov_b32_e32 v25, v0
	v_mov_b32_e32 v26, v0
	v_mov_b32_e32 v27, v0
	v_mov_b32_e32 v28, v0
	v_mov_b32_e32 v29, v0
	v_mov_b32_e32 v30, v0
	v_mov_b32_e32 v31, v0
	v_mov_b32_e32 v40, v0
	v_mov_b32_e32 v41, v0
	v_mov_b32_e32 v42, v0
	v_mov_b32_e32 v43, v0
	v_mov_b32_e32 v44, v0
	v_mov_b32_e32 v45, v0
	v_mov_b32_e32 v46, v0
	v_mov_b32_e32 v47, v0
	v_mov_b32_e32 v56, v0
	v_mov_b32_e32 v57, v0
	v_mov_b32_e32 v58, v0
	v_mov_b32_e32 v59, v0
	v_mov_b32_e32 v60, v0
	v_mov_b32_e32 v61, v0
	v_mov_b32_e32 v62, v0
	v_mov_b32_e32 v63, v0
	v_mov_b32_e32 v64, v0
	v_mov_b32_e32 v65, v0
	v_mov_b32_e32 v66, v0
	v_mov_b32_e32 v67, v0
	v_mov_b32_e32 v68, v0
	v_mov_b32_e32 v69, v0
	v_mov_b32_e32 v70, v0
	v_mov_b32_e32 v71, v0
	v_mov_b32_e32 v80, v0
	v_mov_b32_e32 v81, v0
	v_mov_b32_e32 v82, v0
	v_mov_b32_e32 v83, v0
	v_mov_b32_e32 v84, v0
	v_mov_b32_e32 v85, v0
	v_mov_b32_e32 v86, v0
	v_mov_b32_e32 v87, v0
	v_mov_b32_e32 v96, v0
	v_mov_b32_e32 v97, v0
	v_mov_b32_e32 v98, v0
	v_mov_b32_e32 v99, v0
	v_mov_b32_e32 v100, v0
	v_mov_b32_e32 v101, v0
	v_mov_b32_e32 v102, v0
	v_mov_b32_e32 v103, v0
	v_mov_b32_e32 v112, v0
	v_mov_b32_e32 v113, v0
	v_mov_b32_e32 v114, v0
	v_mov_b32_e32 v115, v0
	v_mov_b32_e32 v116, v0
	v_mov_b32_e32 v117, v0
	v_mov_b32_e32 v118, v0
	v_mov_b32_e32 v119, v0
	v_mov_b32_e32 v72, v0
	v_mov_b32_e32 v73, v0
	v_mov_b32_e32 v74, v0
	v_mov_b32_e32 v75, v0
	v_mov_b32_e32 v76, v0
	v_mov_b32_e32 v77, v0
	v_mov_b32_e32 v78, v0
	v_mov_b32_e32 v79, v0
	v_mov_b32_e32 v88, v0
	v_mov_b32_e32 v89, v0
	v_mov_b32_e32 v90, v0
	v_mov_b32_e32 v91, v0
	v_mov_b32_e32 v92, v0
	v_mov_b32_e32 v93, v0
	v_mov_b32_e32 v94, v0
	v_mov_b32_e32 v95, v0
	v_mov_b32_e32 v104, v0
	v_mov_b32_e32 v105, v0
	v_mov_b32_e32 v106, v0
	v_mov_b32_e32 v107, v0
	v_mov_b32_e32 v108, v0
	v_mov_b32_e32 v109, v0
	v_mov_b32_e32 v110, v0
	v_mov_b32_e32 v111, v0
	v_mov_b32_e32 v120, v0
	v_mov_b32_e32 v121, v0
	v_mov_b32_e32 v122, v0
	v_mov_b32_e32 v123, v0
	v_mov_b32_e32 v124, v0
	v_mov_b32_e32 v125, v0
	v_mov_b32_e32 v126, v0
	v_mov_b32_e32 v127, v0
	v_readlane_b32 s98, v255, 17
	s_cmp_lg_u32 s98, 1
	s_cbranch_scc1 .Lsprio_3
	s_setprio 1
